# v6 plus: o-proj and final down-proj fused epilogues also prefetch the bf16 residual with 16-byte loads (descriptor next_free_vgpr 256 for temporaries v250..v253)
# speedup vs baseline: 1.0290x; 1.0071x over previous
.LBB0_948:
	s_add_u32 s12, s16, 0x3000000
	s_addc_u32 s13, s17, 0
	s_add_u32 s0, s16, 0xfc40000
	s_addc_u32 s1, s17, 0
	s_lshl_b32 s4, s3, 5
	s_lshl_b32 s5, s18, 8
	s_or_b32 s4, s5, s4
	v_lshrrev_b32_e32 v2, 2, v241
	v_and_or_b32 v162, v2, 12, s4
	v_ashrrev_i32_e32 v163, 31, v162
	v_lshlrev_b64 v[2:3], 2, v[162:163]
	v_lshl_add_u64 v[4:5], s[16:17], 0, v[2:3]
	s_mov_b64 s[4:5], 0xfc60000
	v_lshl_add_u64 v[6:7], v[4:5], 0, s[4:5]
	s_mov_b32 s4, 0xfc60000
	v_add_co_u32_e32 v4, vcc, s4, v4
	s_barrier
	s_nop 0
	v_addc_co_u32_e32 v5, vcc, 0, v5, vcc
	global_load_dwordx4 v[154:157], v[6:7], off offset:64
	global_load_dwordx4 v[150:153], v[6:7], off offset:512
	global_load_dwordx4 v[158:161], v[4:5], off
	global_load_dwordx4 v[146:149], v[6:7], off offset:576
	s_lshl_b32 s33, s31, 8
	s_add_i32 s4, s33, s30
	v_or_b32_e32 v4, s4, v235
	v_ashrrev_i32_e32 v5, 31, v4
	v_or_b32_e32 v8, 16, v4
	v_or_b32_e32 v12, 32, v4
	v_or_b32_e32 v16, 48, v4
	v_add_u32_e32 v166, 0x80, v4
	v_add_u32_e32 v170, 0x90, v4
	v_add_u32_e32 v174, 0xa0, v4
	v_add_u32_e32 v228, 0xb0, v4
	v_lshl_add_u64 v[6:7], v[4:5], 2, s[0:1]
	v_ashrrev_i32_e32 v9, 31, v8
	v_ashrrev_i32_e32 v13, 31, v12
	v_ashrrev_i32_e32 v17, 31, v16
	v_ashrrev_i32_e32 v167, 31, v166
	v_ashrrev_i32_e32 v171, 31, v170
	v_ashrrev_i32_e32 v175, 31, v174
	v_ashrrev_i32_e32 v229, 31, v228
	v_lshl_add_u64 v[10:11], v[8:9], 2, s[0:1]
	v_lshl_add_u64 v[14:15], v[12:13], 2, s[0:1]
	v_lshl_add_u64 v[164:165], v[16:17], 2, s[0:1]
	v_lshl_add_u64 v[168:169], v[166:167], 2, s[0:1]
	v_lshl_add_u64 v[172:173], v[170:171], 2, s[0:1]
	v_lshl_add_u64 v[176:177], v[174:175], 2, s[0:1]
	v_lshl_add_u64 v[178:179], v[228:229], 2, s[0:1]
	global_load_dword v246, v[6:7], off
	global_load_dword v244, v[10:11], off
	global_load_dword v242, v[14:15], off
	global_load_dword v240, v[164:165], off
	global_load_dword v238, v[168:169], off
	global_load_dword v236, v[172:173], off
	global_load_dword v234, v[176:177], off
	global_load_dword v232, v[178:179], off
	v_lshl_add_u64 v[6:7], v[162:163], 1, s[12:13]
	v_lshlrev_b64 v[4:5], 11, v[4:5]
	v_lshl_add_u64 v[4:5], v[6:7], 0, v[4:5]
	v_mbcnt_lo_u32_b32 v250, -1, 0
	v_mbcnt_hi_u32_b32 v250, -1, v250
	v_lshrrev_b32_e32 v250, 4, v250
	v_lshlrev_b32_e32 v250, 3, v250
	v_mov_b32_e32 v251, 0
	v_lshl_add_u64 v[252:253], v[4:5], 0, v[250:251]
	global_load_dwordx4 v[224:227], v[252:253], off
	global_load_dwordx4 v[220:223], v[252:253], off offset:256
	v_lshlrev_b64 v[4:5], 11, v[8:9]
	v_lshl_add_u64 v[4:5], v[6:7], 0, v[4:5]
	v_lshl_add_u64 v[252:253], v[4:5], 0, v[250:251]
	global_load_dwordx4 v[216:219], v[252:253], off
	global_load_dwordx4 v[212:215], v[252:253], off offset:256
	v_lshlrev_b64 v[4:5], 11, v[12:13]
	v_lshl_add_u64 v[4:5], v[6:7], 0, v[4:5]
	v_lshl_add_u64 v[252:253], v[4:5], 0, v[250:251]
	global_load_dwordx4 v[208:211], v[252:253], off
	global_load_dwordx4 v[204:207], v[252:253], off offset:256
	v_lshlrev_b64 v[4:5], 11, v[16:17]
	v_lshl_add_u64 v[4:5], v[6:7], 0, v[4:5]
	v_lshl_add_u64 v[252:253], v[4:5], 0, v[250:251]
	global_load_dwordx4 v[200:203], v[252:253], off
	global_load_dwordx4 v[196:199], v[252:253], off offset:256
	v_lshlrev_b64 v[4:5], 11, v[166:167]
	v_lshl_add_u64 v[4:5], v[6:7], 0, v[4:5]
	v_lshl_add_u64 v[252:253], v[4:5], 0, v[250:251]
	global_load_dwordx4 v[192:195], v[252:253], off
	global_load_dwordx4 v[188:191], v[252:253], off offset:256
	v_lshlrev_b64 v[4:5], 11, v[170:171]
	v_lshl_add_u64 v[4:5], v[6:7], 0, v[4:5]
	v_lshl_add_u64 v[252:253], v[4:5], 0, v[250:251]
	global_load_dwordx4 v[184:187], v[252:253], off
	global_load_dwordx4 v[180:183], v[252:253], off offset:256
	v_lshlrev_b64 v[4:5], 11, v[174:175]
	v_lshl_add_u64 v[4:5], v[6:7], 0, v[4:5]
	v_lshl_add_u64 v[252:253], v[4:5], 0, v[250:251]
	global_load_dwordx4 v[176:179], v[252:253], off
	global_load_dwordx4 v[172:175], v[252:253], off offset:256
	v_lshlrev_b64 v[4:5], 11, v[228:229]
	v_lshl_add_u64 v[4:5], v[6:7], 0, v[4:5]
	v_lshl_add_u64 v[2:3], s[22:23], 0, v[2:3]
	v_lshl_add_u64 v[252:253], v[4:5], 0, v[250:251]
	global_load_dwordx4 v[168:171], v[252:253], off
	global_load_dwordx4 v[164:167], v[252:253], off offset:256
	global_load_dwordx4 v[14:17], v[2:3], off
	global_load_dwordx4 v[10:13], v[2:3], off offset:64
	global_load_dwordx4 v[6:9], v[2:3], off offset:512
	s_nop 0
	global_load_dwordx4 v[2:5], v[2:3], off offset:576
	v_and_b32_e32 v243, 63, v241
	s_lshl_b32 s0, s3, 2
	v_cmp_gt_u32_e64 s[4:5], 16, v243
	s_add_i32 s34, s0, 0
	s_waitcnt vmcnt(47)
	v_pk_mul_f32 v[138:139], v[154:155], v[138:139]
	s_waitcnt vmcnt(46)
	v_pk_mul_f32 v[136:137], v[152:153], v[136:137]
	s_waitcnt vmcnt(45)
	v_pk_mul_f32 v[144:145], v[160:161], v[144:145]
	v_pk_mul_f32 v[142:143], v[158:159], v[142:143]
	s_waitcnt vmcnt(44)
	v_pk_mul_f32 v[130:131], v[146:147], v[130:131]
	v_pk_mul_f32 v[140:141], v[156:157], v[140:141]
	v_pk_mul_f32 v[134:135], v[150:151], v[134:135]
	v_pk_mul_f32 v[132:133], v[148:149], v[132:133]
	s_waitcnt vmcnt(43)
	v_pk_mul_f32 v[228:229], v[144:145], v[246:247] op_sel_hi:[1,0]
	v_pk_mul_f32 v[230:231], v[142:143], v[246:247] op_sel_hi:[1,0]
	v_pk_mul_f32 v[144:145], v[138:139], v[246:247] op_sel_hi:[1,0]
	v_pk_mul_f32 v[138:139], v[136:137], v[246:247] op_sel_hi:[1,0]
	v_pk_mul_f32 v[136:137], v[130:131], v[246:247] op_sel_hi:[1,0]
	v_mul_f32_e32 v130, v231, v231
	v_mul_f32_e32 v131, v229, v229
	v_pk_mul_f32 v[142:143], v[140:141], v[246:247] op_sel_hi:[1,0]
	v_fmac_f32_e32 v130, v230, v230
	v_fmac_f32_e32 v131, v228, v228
	v_pk_mul_f32 v[140:141], v[134:135], v[246:247] op_sel_hi:[1,0]
	v_pk_mul_f32 v[134:135], v[132:133], v[246:247] op_sel_hi:[1,0]
	v_add_f32_e32 v130, v130, v131
	v_mul_f32_e32 v131, v145, v145
	v_mul_f32_e32 v132, v143, v143
	v_fmac_f32_e32 v131, v144, v144
	v_fmac_f32_e32 v132, v142, v142
	v_add_f32_e32 v131, v131, v132
	v_add_f32_e32 v130, v130, v131
	v_mul_f32_e32 v131, v141, v141
	v_mul_f32_e32 v132, v139, v139
	v_fmac_f32_e32 v131, v140, v140
	v_fmac_f32_e32 v132, v138, v138
	v_add_f32_e32 v131, v131, v132
	v_add_f32_e32 v130, v131, v130
	v_mul_f32_e32 v131, v137, v137
	v_mul_f32_e32 v132, v135, v135
	v_fmac_f32_e32 v131, v136, v136
	v_fmac_f32_e32 v132, v134, v134
	v_add_f32_e32 v131, v131, v132
	v_add_f32_e32 v130, v131, v130
	ds_bpermute_b32 v131, v1, v130
	s_waitcnt lgkmcnt(0)
	v_add_f32_e32 v130, v130, v131
	ds_bpermute_b32 v131, v233, v130
	s_and_saveexec_b64 s[0:1], s[4:5]
	s_cbranch_execz .LBB0_950
	s_lshl_b32 s3, s2, 10
	s_add_i32 s3, s34, s3
	v_lshl_add_u32 v132, v235, 4, s3
	s_waitcnt lgkmcnt(0)
	v_add_f32_e32 v130, v130, v131
	ds_write_b32 v132, v130

.LBB0_978:
	s_or_b64 exec, exec, s[0:1]
	s_waitcnt vmcnt(0) lgkmcnt(0)
	s_barrier
	v_permlane16_swap_b32_e32 v224, v226
	v_permlane16_swap_b32_e32 v225, v227
	v_permlane16_swap_b32_e32 v220, v222
	v_permlane16_swap_b32_e32 v221, v223
	v_permlane16_swap_b32_e32 v216, v218
	v_permlane16_swap_b32_e32 v217, v219
	v_permlane16_swap_b32_e32 v212, v214
	v_permlane16_swap_b32_e32 v213, v215
	v_permlane16_swap_b32_e32 v208, v210
	v_permlane16_swap_b32_e32 v209, v211
	v_permlane16_swap_b32_e32 v204, v206
	v_permlane16_swap_b32_e32 v205, v207
	v_permlane16_swap_b32_e32 v200, v202
	v_permlane16_swap_b32_e32 v201, v203
	v_permlane16_swap_b32_e32 v196, v198
	v_permlane16_swap_b32_e32 v197, v199
	v_permlane16_swap_b32_e32 v192, v194
	v_permlane16_swap_b32_e32 v193, v195
	v_permlane16_swap_b32_e32 v188, v190
	v_permlane16_swap_b32_e32 v189, v191
	v_permlane16_swap_b32_e32 v184, v186
	v_permlane16_swap_b32_e32 v185, v187
	v_permlane16_swap_b32_e32 v180, v182
	v_permlane16_swap_b32_e32 v181, v183
	v_permlane16_swap_b32_e32 v176, v178
	v_permlane16_swap_b32_e32 v177, v179
	v_permlane16_swap_b32_e32 v172, v174
	v_permlane16_swap_b32_e32 v173, v175
	v_permlane16_swap_b32_e32 v168, v170
	v_permlane16_swap_b32_e32 v169, v171
	v_permlane16_swap_b32_e32 v164, v166
	v_permlane16_swap_b32_e32 v165, v167
	v_permlane32_swap_b32_e32 v224, v226
	v_permlane32_swap_b32_e32 v225, v227
	v_permlane32_swap_b32_e32 v220, v222
	v_permlane32_swap_b32_e32 v221, v223
	v_permlane32_swap_b32_e32 v216, v218
	v_permlane32_swap_b32_e32 v217, v219
	v_permlane32_swap_b32_e32 v212, v214
	v_permlane32_swap_b32_e32 v213, v215
	v_permlane32_swap_b32_e32 v208, v210
	v_permlane32_swap_b32_e32 v209, v211
	v_permlane32_swap_b32_e32 v204, v206
	v_permlane32_swap_b32_e32 v205, v207
	v_permlane32_swap_b32_e32 v200, v202
	v_permlane32_swap_b32_e32 v201, v203
	v_permlane32_swap_b32_e32 v196, v198
	v_permlane32_swap_b32_e32 v197, v199
	v_permlane32_swap_b32_e32 v192, v194
	v_permlane32_swap_b32_e32 v193, v195
	v_permlane32_swap_b32_e32 v188, v190
	v_permlane32_swap_b32_e32 v189, v191
	v_permlane32_swap_b32_e32 v184, v186
	v_permlane32_swap_b32_e32 v185, v187
	v_permlane32_swap_b32_e32 v180, v182
	v_permlane32_swap_b32_e32 v181, v183
	v_permlane32_swap_b32_e32 v176, v178
	v_permlane32_swap_b32_e32 v177, v179
	v_permlane32_swap_b32_e32 v172, v174
	v_permlane32_swap_b32_e32 v173, v175
	v_permlane32_swap_b32_e32 v168, v170
	v_permlane32_swap_b32_e32 v169, v171
	v_permlane32_swap_b32_e32 v164, v166
	v_permlane32_swap_b32_e32 v165, v167
	v_swap_b32 v224, v226
	v_swap_b32 v225, v227
	v_swap_b32 v220, v222
	v_swap_b32 v221, v223
	v_swap_b32 v216, v218
	v_swap_b32 v217, v219
	v_swap_b32 v212, v214
	v_swap_b32 v213, v215
	v_swap_b32 v208, v210
	v_swap_b32 v209, v211
	v_swap_b32 v204, v206
	v_swap_b32 v205, v207
	v_swap_b32 v200, v202
	v_swap_b32 v201, v203
	v_swap_b32 v196, v198
	v_swap_b32 v197, v199
	v_swap_b32 v192, v194
	v_swap_b32 v193, v195
	v_swap_b32 v188, v190
	v_swap_b32 v189, v191
	v_swap_b32 v184, v186
	v_swap_b32 v185, v187
	v_swap_b32 v180, v182
	v_swap_b32 v181, v183
	v_swap_b32 v176, v178
	v_swap_b32 v177, v179
	v_swap_b32 v172, v174
	v_swap_b32 v173, v175
	v_swap_b32 v168, v170
	v_swap_b32 v169, v171
	v_swap_b32 v164, v166
	v_swap_b32 v165, v167
	v_mov_b32_e32 v18, 0
	s_waitcnt lgkmcnt(0)
	ds_read_b32 v19, v18 offset:10240
	v_lshl_add_u32 v18, v237, 2, 0
	ds_read_b32 v20, v18 offset:8192
	v_add_u32_e32 v146, s33, v237
	v_ashrrev_i32_e32 v147, 31, v146
	s_waitcnt lgkmcnt(1)
	v_or_b32_e32 v21, v19, v239
	v_lshlrev_b64 v[146:147], 11, v[146:147]
	s_waitcnt vmcnt(35)
	v_lshlrev_b32_e32 v148, 16, v226
	v_and_b32_e32 v149, 0xffff0000, v226
	v_lshlrev_b32_e32 v150, 16, v227
	v_and_b32_e32 v151, 0xffff0000, v227
	s_waitcnt lgkmcnt(0)
	v_pk_mul_f32 v[152:153], v[228:229], v[20:21] op_sel_hi:[1,0]
	v_pk_mul_f32 v[154:155], v[230:231], v[20:21] op_sel_hi:[1,0]
	s_waitcnt vmcnt(3)
	v_pk_fma_f32 v[150:151], v[16:17], v[152:153], v[150:151]
	v_pk_fma_f32 v[148:149], v[14:15], v[154:155], v[148:149]
	v_mov_b32_e32 v19, 0x7fc00000
	v_cmp_ne_u32_e32 vcc, 0, v21
	v_lshl_add_u64 v[146:147], s[12:13], 0, v[146:147]
	v_lshl_add_u64 v[146:147], v[162:163], 1, v[146:147]
	v_cndmask_b32_e32 v21, v150, v19, vcc
	v_cndmask_b32_e32 v150, v151, v19, vcc
	v_cndmask_b32_e32 v151, v148, v19, vcc
	v_cndmask_b32_e32 v152, v149, v19, vcc
	v_cvt_pk_bf16_f32 v148, v151, v152
	v_cvt_pk_bf16_f32 v149, v21, v150
	v_mbcnt_lo_u32_b32 v160, -1, 0
	v_mbcnt_hi_u32_b32 v160, -1, v160
	v_lshrrev_b32_e32 v160, 4, v160
	v_lshlrev_b32_e32 v160, 3, v160
	v_mov_b32_e32 v161, 0
	v_mov_b32_e32 v244, v148
	v_mov_b32_e32 v245, v149
	v_mul_f32_e32 v148, v152, v152
	v_mul_f32_e32 v149, v150, v150
	v_fmac_f32_e32 v148, v151, v151
	v_fmac_f32_e32 v149, v21, v21
	v_add_f32_e32 v21, v148, v149
	v_lshlrev_b32_e32 v148, 16, v224
	v_and_b32_e32 v149, 0xffff0000, v224
	v_pk_mul_f32 v[144:145], v[144:145], v[20:21] op_sel_hi:[1,0]
	v_lshlrev_b32_e32 v150, 16, v225
	v_and_b32_e32 v151, 0xffff0000, v225
	v_pk_mul_f32 v[142:143], v[142:143], v[20:21] op_sel_hi:[1,0]
	s_waitcnt vmcnt(3)
	v_pk_fma_f32 v[144:145], v[10:11], v[144:145], v[148:149]
	v_pk_fma_f32 v[142:143], v[12:13], v[142:143], v[150:151]
	v_cndmask_b32_e32 v145, v145, v19, vcc
	v_cndmask_b32_e32 v150, v142, v19, vcc
	v_cndmask_b32_e32 v143, v143, v19, vcc
	v_cndmask_b32_e32 v144, v144, v19, vcc
	v_cvt_pk_bf16_f32 v142, v144, v145
	v_mul_f32_e32 v145, v145, v145
	v_fmac_f32_e32 v145, v144, v144
	v_mul_f32_e32 v144, v143, v143
	v_fmac_f32_e32 v144, v150, v150
	v_add_f32_e32 v144, v145, v144
	v_add_f32_e32 v21, v21, v144
	v_lshlrev_b32_e32 v144, 16, v222
	v_and_b32_e32 v145, 0xffff0000, v222
	v_lshlrev_b32_e32 v148, 16, v223
	v_and_b32_e32 v149, 0xffff0000, v223
	v_pk_mul_f32 v[138:139], v[138:139], v[20:21] op_sel_hi:[1,0]
	v_pk_mul_f32 v[140:141], v[140:141], v[20:21] op_sel_hi:[1,0]
	s_waitcnt vmcnt(2)
	v_pk_fma_f32 v[138:139], v[8:9], v[138:139], v[148:149]
	v_pk_fma_f32 v[140:141], v[6:7], v[140:141], v[144:145]
	v_cndmask_b32_e32 v145, v139, v19, vcc
	v_cndmask_b32_e32 v149, v141, v19, vcc
	v_cndmask_b32_e32 v144, v138, v19, vcc
	v_cndmask_b32_e32 v148, v140, v19, vcc
	v_mul_f32_e32 v138, v149, v149
	v_mul_f32_e32 v139, v145, v145
	v_fmac_f32_e32 v138, v148, v148
	v_fmac_f32_e32 v139, v144, v144
	v_add_f32_e32 v138, v138, v139
	v_add_f32_e32 v151, v138, v21
	v_lshlrev_b32_e32 v138, 16, v220
	v_and_b32_e32 v139, 0xffff0000, v220
	v_lshlrev_b32_e32 v140, 16, v221
	v_and_b32_e32 v141, 0xffff0000, v221
	v_pk_mul_f32 v[134:135], v[134:135], v[20:21] op_sel_hi:[1,0]
	v_pk_mul_f32 v[20:21], v[136:137], v[20:21] op_sel_hi:[1,0]
	s_waitcnt vmcnt(1)
	v_pk_fma_f32 v[134:135], v[4:5], v[134:135], v[140:141]
	v_pk_fma_f32 v[20:21], v[2:3], v[20:21], v[138:139]
	v_cndmask_b32_e32 v137, v135, v19, vcc
	v_cndmask_b32_e32 v139, v21, v19, vcc
	v_cndmask_b32_e32 v136, v134, v19, vcc
	v_cndmask_b32_e32 v138, v20, v19, vcc
	v_mul_f32_e32 v20, v139, v139
	v_mul_f32_e32 v21, v137, v137
	v_fmac_f32_e32 v20, v138, v138
	v_fmac_f32_e32 v21, v136, v136
	v_add_f32_e32 v20, v20, v21
	v_add_f32_e32 v20, v20, v151
	ds_bpermute_b32 v21, v1, v20
	v_cvt_pk_bf16_f32 v143, v150, v143
	v_mov_b32_e32 v246, v142
	v_mov_b32_e32 v247, v143
	s_nop 1
	v_permlane32_swap_b32_e32 v244, v246
	v_permlane32_swap_b32_e32 v245, v247
	s_nop 0
	v_permlane16_swap_b32_e32 v244, v246
	v_permlane16_swap_b32_e32 v245, v247
	v_lshl_add_u64 v[240:241], v[146:147], 0, v[160:161]
	global_store_dwordx4 v[240:241], v[244:247], off
	v_cvt_pk_bf16_f32 v134, v148, v149
	v_cvt_pk_bf16_f32 v135, v144, v145
	s_waitcnt lgkmcnt(0)
	v_add_f32_e32 v20, v20, v21
	ds_bpermute_b32 v21, v233, v20
	v_mov_b32_e32 v156, v134
	v_mov_b32_e32 v157, v135
	v_cvt_pk_bf16_f32 v134, v138, v139
	v_cvt_pk_bf16_f32 v135, v136, v137
	v_mov_b32_e32 v158, v134
	v_mov_b32_e32 v159, v135
	s_nop 1
	v_permlane32_swap_b32_e32 v156, v158
	v_permlane32_swap_b32_e32 v157, v159
	s_nop 0
	v_permlane16_swap_b32_e32 v156, v158
	v_permlane16_swap_b32_e32 v157, v159
	v_lshl_add_u64 v[240:241], v[146:147], 0, v[160:161]
	global_store_dwordx4 v[240:241], v[156:159], off offset:256
	s_and_saveexec_b64 s[0:1], s[4:5]
	s_cbranch_execz .LBB0_980
	v_lshl_add_u32 v134, v237, 4, s34
	s_waitcnt lgkmcnt(0)
	v_add_f32_e32 v20, v20, v21
	ds_write_b32 v134, v20 offset:16384

.LBB0_1144:
	s_lshl_b32 s0, s31, 5
	s_lshl_b32 s1, s20, 8
	s_or_b32 s0, s1, s0
	v_lshrrev_b32_e32 v130, 2, v0
	s_lshl_b32 s27, s25, 8
	v_and_or_b32 v210, v130, 12, s0
	s_add_i32 s0, s27, s24
	v_or_b32_e32 v130, s0, v221
	v_ashrrev_i32_e32 v211, 31, v210
	v_lshl_add_u64 v[132:133], v[210:211], 1, s[10:11]
	s_mov_b64 s[0:1], 0x3000000
	v_ashrrev_i32_e32 v131, 31, v130
	v_lshl_add_u64 v[132:133], v[132:133], 0, s[0:1]
	v_lshlrev_b64 v[134:135], 11, v[130:131]
	v_lshl_add_u64 v[134:135], v[132:133], 0, v[134:135]
	s_barrier
	v_mbcnt_lo_u32_b32 v238, -1, 0
	v_mbcnt_hi_u32_b32 v238, -1, v238
	v_lshrrev_b32_e32 v238, 4, v238
	v_lshlrev_b32_e32 v238, 3, v238
	v_mov_b32_e32 v239, 0
	v_lshl_add_u64 v[236:237], v[134:135], 0, v[238:239]
	global_load_dwordx4 v[212:215], v[236:237], off
	global_load_dwordx4 v[206:209], v[236:237], off offset:256
	v_or_b32_e32 v134, 16, v130
	v_ashrrev_i32_e32 v135, 31, v134
	v_lshlrev_b64 v[134:135], 11, v[134:135]
	v_lshl_add_u64 v[134:135], v[132:133], 0, v[134:135]
	v_lshl_add_u64 v[236:237], v[134:135], 0, v[238:239]
	global_load_dwordx4 v[202:205], v[236:237], off
	global_load_dwordx4 v[198:201], v[236:237], off offset:256
	v_or_b32_e32 v134, 32, v130
	v_ashrrev_i32_e32 v135, 31, v134
	v_lshlrev_b64 v[134:135], 11, v[134:135]
	v_lshl_add_u64 v[134:135], v[132:133], 0, v[134:135]
	v_lshl_add_u64 v[236:237], v[134:135], 0, v[238:239]
	global_load_dwordx4 v[194:197], v[236:237], off
	global_load_dwordx4 v[190:193], v[236:237], off offset:256
	v_or_b32_e32 v134, 48, v130
	v_ashrrev_i32_e32 v135, 31, v134
	v_lshlrev_b64 v[134:135], 11, v[134:135]
	v_lshl_add_u64 v[134:135], v[132:133], 0, v[134:135]
	v_lshl_add_u64 v[236:237], v[134:135], 0, v[238:239]
	global_load_dwordx4 v[186:189], v[236:237], off
	global_load_dwordx4 v[182:185], v[236:237], off offset:256
	v_add_u32_e32 v134, 0x80, v130
	v_ashrrev_i32_e32 v135, 31, v134
	v_lshlrev_b64 v[134:135], 11, v[134:135]
	v_lshl_add_u64 v[134:135], v[132:133], 0, v[134:135]
	v_lshl_add_u64 v[236:237], v[134:135], 0, v[238:239]
	global_load_dwordx4 v[178:181], v[236:237], off
	global_load_dwordx4 v[174:177], v[236:237], off offset:256
	v_add_u32_e32 v134, 0x90, v130
	v_ashrrev_i32_e32 v135, 31, v134
	v_lshlrev_b64 v[134:135], 11, v[134:135]
	v_lshl_add_u64 v[134:135], v[132:133], 0, v[134:135]
	v_lshl_add_u64 v[236:237], v[134:135], 0, v[238:239]
	global_load_dwordx4 v[170:173], v[236:237], off
	global_load_dwordx4 v[166:169], v[236:237], off offset:256
	v_add_u32_e32 v134, 0xa0, v130
	v_add_u32_e32 v130, 0xb0, v130
	v_ashrrev_i32_e32 v135, 31, v134
	v_ashrrev_i32_e32 v131, 31, v130
	v_lshlrev_b64 v[134:135], 11, v[134:135]
	v_lshlrev_b64 v[130:131], 11, v[130:131]
	v_lshl_add_u64 v[134:135], v[132:133], 0, v[134:135]
	v_lshl_add_u64 v[130:131], v[132:133], 0, v[130:131]
	v_lshl_add_u64 v[236:237], v[134:135], 0, v[238:239]
	global_load_dwordx4 v[162:165], v[236:237], off
	global_load_dwordx4 v[158:161], v[236:237], off offset:256
	v_lshl_add_u64 v[236:237], v[130:131], 0, v[238:239]
	global_load_dwordx4 v[154:157], v[236:237], off
	global_load_dwordx4 v[150:153], v[236:237], off offset:256
	v_lshl_add_u64 v[130:131], v[210:211], 2, s[22:23]
	s_mov_b64 s[0:1], 0x1000
	v_lshl_add_u64 v[132:133], v[130:131], 0, s[0:1]
	s_movk_i32 s0, 0x1000
	v_add_co_u32_e32 v130, vcc, s0, v130
	v_mul_f32_e32 v146, v127, v127
	s_nop 0
	v_addc_co_u32_e32 v131, vcc, 0, v131, vcc
	global_load_dwordx4 v[138:141], v[132:133], off offset:64
	global_load_dwordx4 v[134:137], v[132:133], off offset:512
	global_load_dwordx4 v[142:145], v[130:131], off
	s_nop 0
	global_load_dwordx4 v[130:133], v[132:133], off offset:576
	v_mul_f32_e32 v147, v129, v129
	v_fmac_f32_e32 v146, v126, v126
	v_fmac_f32_e32 v147, v128, v128
	v_add_f32_e32 v146, v146, v147
	v_mul_f32_e32 v147, v123, v123
	v_mul_f32_e32 v148, v125, v125
	v_fmac_f32_e32 v147, v122, v122
	v_fmac_f32_e32 v148, v124, v124
	v_add_f32_e32 v147, v147, v148
	v_add_f32_e32 v146, v147, v146
	v_mul_f32_e32 v147, v115, v115
	v_mul_f32_e32 v148, v117, v117
	v_fmac_f32_e32 v147, v114, v114
	v_fmac_f32_e32 v148, v116, v116
	v_add_f32_e32 v147, v147, v148
	v_add_f32_e32 v146, v147, v146
	v_mul_f32_e32 v147, v111, v111
	v_mul_f32_e32 v148, v113, v113
	v_fmac_f32_e32 v147, v110, v110
	v_fmac_f32_e32 v148, v112, v112
	v_add_f32_e32 v147, v147, v148
	v_add_f32_e32 v146, v147, v146
	ds_bpermute_b32 v147, v1, v146
	s_lshl_b32 s0, s31, 2
	s_add_i32 s2, s0, 0
	s_waitcnt lgkmcnt(0)
	v_add_f32_e32 v147, v146, v147
	ds_bpermute_b32 v148, v233, v147
	v_and_b32_e32 v146, 63, v0
	v_cmp_gt_u32_e32 vcc, 16, v146
	s_and_saveexec_b64 s[0:1], vcc
	s_cbranch_execz .LBB0_1146
	s_lshl_b32 s3, s26, 10
	s_add_i32 s3, s2, s3
	v_lshl_add_u32 v149, v221, 4, s3
	s_waitcnt lgkmcnt(0)
	v_add_f32_e32 v147, v147, v148
	ds_write_b32 v149, v147

.LBB0_1174:
	s_or_b64 exec, exec, s[4:5]
	s_waitcnt vmcnt(0) lgkmcnt(0)
	s_barrier
	v_permlane16_swap_b32_e32 v212, v214
	v_permlane16_swap_b32_e32 v213, v215
	v_permlane16_swap_b32_e32 v206, v208
	v_permlane16_swap_b32_e32 v207, v209
	v_permlane16_swap_b32_e32 v202, v204
	v_permlane16_swap_b32_e32 v203, v205
	v_permlane16_swap_b32_e32 v198, v200
	v_permlane16_swap_b32_e32 v199, v201
	v_permlane16_swap_b32_e32 v194, v196
	v_permlane16_swap_b32_e32 v195, v197
	v_permlane16_swap_b32_e32 v190, v192
	v_permlane16_swap_b32_e32 v191, v193
	v_permlane16_swap_b32_e32 v186, v188
	v_permlane16_swap_b32_e32 v187, v189
	v_permlane16_swap_b32_e32 v182, v184
	v_permlane16_swap_b32_e32 v183, v185
	v_permlane16_swap_b32_e32 v178, v180
	v_permlane16_swap_b32_e32 v179, v181
	v_permlane16_swap_b32_e32 v174, v176
	v_permlane16_swap_b32_e32 v175, v177
	v_permlane16_swap_b32_e32 v170, v172
	v_permlane16_swap_b32_e32 v171, v173
	v_permlane16_swap_b32_e32 v166, v168
	v_permlane16_swap_b32_e32 v167, v169
	v_permlane16_swap_b32_e32 v162, v164
	v_permlane16_swap_b32_e32 v163, v165
	v_permlane16_swap_b32_e32 v158, v160
	v_permlane16_swap_b32_e32 v159, v161
	v_permlane16_swap_b32_e32 v154, v156
	v_permlane16_swap_b32_e32 v155, v157
	v_permlane16_swap_b32_e32 v150, v152
	v_permlane16_swap_b32_e32 v151, v153
	v_permlane32_swap_b32_e32 v212, v214
	v_permlane32_swap_b32_e32 v213, v215
	v_permlane32_swap_b32_e32 v206, v208
	v_permlane32_swap_b32_e32 v207, v209
	v_permlane32_swap_b32_e32 v202, v204
	v_permlane32_swap_b32_e32 v203, v205
	v_permlane32_swap_b32_e32 v198, v200
	v_permlane32_swap_b32_e32 v199, v201
	v_permlane32_swap_b32_e32 v194, v196
	v_permlane32_swap_b32_e32 v195, v197
	v_permlane32_swap_b32_e32 v190, v192
	v_permlane32_swap_b32_e32 v191, v193
	v_permlane32_swap_b32_e32 v186, v188
	v_permlane32_swap_b32_e32 v187, v189
	v_permlane32_swap_b32_e32 v182, v184
	v_permlane32_swap_b32_e32 v183, v185
	v_permlane32_swap_b32_e32 v178, v180
	v_permlane32_swap_b32_e32 v179, v181
	v_permlane32_swap_b32_e32 v174, v176
	v_permlane32_swap_b32_e32 v175, v177
	v_permlane32_swap_b32_e32 v170, v172
	v_permlane32_swap_b32_e32 v171, v173
	v_permlane32_swap_b32_e32 v166, v168
	v_permlane32_swap_b32_e32 v167, v169
	v_permlane32_swap_b32_e32 v162, v164
	v_permlane32_swap_b32_e32 v163, v165
	v_permlane32_swap_b32_e32 v158, v160
	v_permlane32_swap_b32_e32 v159, v161
	v_permlane32_swap_b32_e32 v154, v156
	v_permlane32_swap_b32_e32 v155, v157
	v_permlane32_swap_b32_e32 v150, v152
	v_permlane32_swap_b32_e32 v151, v153
	v_swap_b32 v212, v214
	v_swap_b32 v213, v215
	v_swap_b32 v206, v208
	v_swap_b32 v207, v209
	v_swap_b32 v202, v204
	v_swap_b32 v203, v205
	v_swap_b32 v198, v200
	v_swap_b32 v199, v201
	v_swap_b32 v194, v196
	v_swap_b32 v195, v197
	v_swap_b32 v190, v192
	v_swap_b32 v191, v193
	v_swap_b32 v186, v188
	v_swap_b32 v187, v189
	v_swap_b32 v182, v184
	v_swap_b32 v183, v185
	v_swap_b32 v178, v180
	v_swap_b32 v179, v181
	v_swap_b32 v174, v176
	v_swap_b32 v175, v177
	v_swap_b32 v170, v172
	v_swap_b32 v171, v173
	v_swap_b32 v166, v168
	v_swap_b32 v167, v169
	v_swap_b32 v162, v164
	v_swap_b32 v163, v165
	v_swap_b32 v158, v160
	v_swap_b32 v159, v161
	v_swap_b32 v154, v156
	v_swap_b32 v155, v157
	v_swap_b32 v150, v152
	v_swap_b32 v151, v153
	v_mov_b32_e32 v0, 0
	ds_read_b32 v1, v0 offset:10240
	s_waitcnt lgkmcnt(0)
	v_lshl_add_u32 v147, v222, 2, 0
	v_add_u32_e32 v0, s24, v221
	v_lshl_add_u32 v148, v0, 2, 0
	ds_read_b32 v0, v147 offset:8832
	ds_read_b32 v146, v148 offset:8896
	v_add_u32_e32 v147, 0x2000, v147
	ds_read2_b32 v[218:219], v147 offset1:16
	s_waitcnt vmcnt(36)
	v_or_b32_e32 v1, v1, v220
	v_add_u32_e32 v222, s27, v222
	s_waitcnt vmcnt(35)
	v_lshlrev_b32_e32 v216, 16, v214
	v_and_b32_e32 v217, 0xffff0000, v214
	s_waitcnt lgkmcnt(0)
	v_pk_mul_f32 v[126:127], v[126:127], v[218:219] op_sel_hi:[1,0]
	v_ashrrev_i32_e32 v223, 31, v222
	v_lshlrev_b32_e32 v214, 16, v215
	v_and_b32_e32 v215, 0xffff0000, v215
	v_pk_mul_f32 v[128:129], v[128:129], v[218:219] op_sel_hi:[1,0]
	s_waitcnt vmcnt(1)
	v_pk_fma_f32 v[126:127], v[142:143], v[126:127], v[216:217]
	v_mov_b32_e32 v149, 0x7fc00000
	v_cmp_ne_u32_e32 vcc, 0, v1
	v_lshlrev_b64 v[224:225], 12, v[222:223]
	v_pk_fma_f32 v[128:129], v[144:145], v[128:129], v[214:215]
	v_cndmask_b32_e32 v215, v127, v149, vcc
	v_cndmask_b32_e32 v214, v126, v149, vcc
	v_lshlrev_b64 v[126:127], 2, v[210:211]
	v_lshlrev_b32_e32 v210, 16, v212
	v_and_b32_e32 v211, 0xffff0000, v212
	v_lshlrev_b32_e32 v212, 16, v213
	v_and_b32_e32 v213, 0xffff0000, v213
	v_pk_mul_f32 v[124:125], v[124:125], v[218:219] op_sel_hi:[1,0]
	v_pk_mul_f32 v[122:123], v[122:123], v[218:219] op_sel_hi:[1,0]
	v_cndmask_b32_e32 v217, v129, v149, vcc
	v_cndmask_b32_e32 v216, v128, v149, vcc
	v_lshl_add_u64 v[128:129], s[8:9], 0, v[224:225]
	v_pk_fma_f32 v[122:123], v[138:139], v[122:123], v[210:211]
	v_pk_fma_f32 v[124:125], v[140:141], v[124:125], v[212:213]
	v_lshl_add_u64 v[128:129], v[128:129], 0, v[126:127]
	v_cndmask_b32_e32 v125, v125, v149, vcc
	v_cndmask_b32_e32 v124, v124, v149, vcc
	v_cndmask_b32_e32 v123, v123, v149, vcc
	v_cndmask_b32_e32 v122, v122, v149, vcc
	global_store_dwordx4 v[128:129], v[122:125], off offset:64
	v_pk_mul_f32 v[116:117], v[116:117], v[218:219] op_sel_hi:[1,0]
	v_pk_mul_f32 v[114:115], v[114:115], v[218:219] op_sel_hi:[1,0]
	v_lshlrev_b32_e32 v122, 16, v208
	v_and_b32_e32 v123, 0xffff0000, v208
	v_lshlrev_b32_e32 v124, 16, v209
	v_and_b32_e32 v125, 0xffff0000, v209
	v_pk_fma_f32 v[114:115], v[134:135], v[114:115], v[122:123]
	v_pk_fma_f32 v[116:117], v[136:137], v[116:117], v[124:125]
	v_cndmask_b32_e32 v115, v115, v149, vcc
	v_cndmask_b32_e32 v117, v117, v149, vcc
	v_cndmask_b32_e32 v116, v116, v149, vcc
	v_cndmask_b32_e32 v114, v114, v149, vcc
	global_store_dwordx4 v[128:129], v[114:117], off offset:512
	v_pk_mul_f32 v[112:113], v[112:113], v[218:219] op_sel_hi:[1,0]
	v_pk_mul_f32 v[110:111], v[110:111], v[218:219] op_sel_hi:[1,0]
	v_lshlrev_b32_e32 v114, 16, v206
	v_and_b32_e32 v115, 0xffff0000, v206
	v_lshlrev_b32_e32 v116, 16, v207
	v_and_b32_e32 v117, 0xffff0000, v207
	s_waitcnt vmcnt(2)
	v_pk_fma_f32 v[110:111], v[130:131], v[110:111], v[114:115]
	v_pk_fma_f32 v[112:113], v[132:133], v[112:113], v[116:117]
	v_cndmask_b32_e32 v111, v111, v149, vcc
	v_cndmask_b32_e32 v113, v113, v149, vcc
	v_cndmask_b32_e32 v112, v112, v149, vcc
	v_cndmask_b32_e32 v110, v110, v149, vcc
	global_store_dwordx4 v[128:129], v[110:113], off offset:576
	v_mov_b32_e32 v116, v219
	v_pk_mul_f32 v[120:121], v[120:121], v[116:117] op_sel_hi:[1,0]
	v_add_u32_e32 v110, 16, v222
	v_ashrrev_i32_e32 v111, 31, v110
	v_lshlrev_b64 v[114:115], 12, v[110:111]
	v_lshlrev_b32_e32 v110, 16, v204
	v_and_b32_e32 v111, 0xffff0000, v204
	v_lshlrev_b32_e32 v112, 16, v205
	v_and_b32_e32 v113, 0xffff0000, v205
	v_pk_mul_f32 v[118:119], v[118:119], v[116:117] op_sel_hi:[1,0]
	v_pk_fma_f32 v[112:113], v[144:145], v[120:121], v[112:113]
	v_pk_fma_f32 v[110:111], v[142:143], v[118:119], v[110:111]
	v_lshl_add_u64 v[114:115], s[8:9], 0, v[114:115]
	v_cndmask_b32_e32 v113, v113, v149, vcc
	v_cndmask_b32_e32 v112, v112, v149, vcc
	v_cndmask_b32_e32 v111, v111, v149, vcc
	v_cndmask_b32_e32 v110, v110, v149, vcc
	v_lshl_add_u64 v[114:115], v[114:115], 0, v[126:127]
	global_store_dwordx4 v[114:115], v[110:113], off
	v_pk_mul_f32 v[108:109], v[108:109], v[116:117] op_sel_hi:[1,0]
	v_pk_mul_f32 v[106:107], v[106:107], v[116:117] op_sel_hi:[1,0]
	v_lshlrev_b32_e32 v110, 16, v202
	v_and_b32_e32 v111, 0xffff0000, v202
	v_lshlrev_b32_e32 v112, 16, v203
	v_and_b32_e32 v113, 0xffff0000, v203
	v_pk_fma_f32 v[106:107], v[138:139], v[106:107], v[110:111]
	v_pk_fma_f32 v[108:109], v[140:141], v[108:109], v[112:113]
	v_cndmask_b32_e32 v107, v107, v149, vcc
	v_cndmask_b32_e32 v109, v109, v149, vcc
	v_cndmask_b32_e32 v108, v108, v149, vcc
	v_cndmask_b32_e32 v106, v106, v149, vcc
	global_store_dwordx4 v[114:115], v[106:109], off offset:64
	v_pk_mul_f32 v[100:101], v[100:101], v[116:117] op_sel_hi:[1,0]
	v_pk_mul_f32 v[98:99], v[98:99], v[116:117] op_sel_hi:[1,0]
	v_lshlrev_b32_e32 v106, 16, v200
	v_and_b32_e32 v107, 0xffff0000, v200
	v_lshlrev_b32_e32 v108, 16, v201
	v_and_b32_e32 v109, 0xffff0000, v201
	v_pk_fma_f32 v[98:99], v[134:135], v[98:99], v[106:107]
	v_pk_fma_f32 v[100:101], v[136:137], v[100:101], v[108:109]
	v_cndmask_b32_e32 v99, v99, v149, vcc
	v_cndmask_b32_e32 v101, v101, v149, vcc
	v_cndmask_b32_e32 v100, v100, v149, vcc
	v_cndmask_b32_e32 v98, v98, v149, vcc
	global_store_dwordx4 v[114:115], v[98:101], off offset:512
	v_pk_mul_f32 v[94:95], v[94:95], v[116:117] op_sel_hi:[1,0]
	v_pk_mul_f32 v[96:97], v[96:97], v[116:117] op_sel_hi:[1,0]
	v_lshlrev_b32_e32 v98, 16, v198
	v_and_b32_e32 v99, 0xffff0000, v198
	v_lshlrev_b32_e32 v100, 16, v199
	v_and_b32_e32 v101, 0xffff0000, v199
	v_pk_fma_f32 v[94:95], v[130:131], v[94:95], v[98:99]
	ds_read2_b32 v[98:99], v147 offset0:32 offset1:48
	v_pk_fma_f32 v[96:97], v[132:133], v[96:97], v[100:101]
	v_cndmask_b32_e32 v95, v95, v149, vcc
	v_cndmask_b32_e32 v97, v97, v149, vcc
	v_cndmask_b32_e32 v96, v96, v149, vcc
	v_cndmask_b32_e32 v94, v94, v149, vcc
	global_store_dwordx4 v[114:115], v[94:97], off offset:576
	s_waitcnt lgkmcnt(0)
	v_pk_mul_f32 v[104:105], v[104:105], v[98:99] op_sel_hi:[1,0]
	v_pk_mul_f32 v[102:103], v[102:103], v[98:99] op_sel_hi:[1,0]
	v_add_u32_e32 v94, 32, v222
	v_ashrrev_i32_e32 v95, 31, v94
	v_lshlrev_b64 v[100:101], 12, v[94:95]
	v_lshlrev_b32_e32 v94, 16, v196
	v_and_b32_e32 v95, 0xffff0000, v196
	v_lshlrev_b32_e32 v96, 16, v197
	v_and_b32_e32 v97, 0xffff0000, v197
	v_pk_fma_f32 v[94:95], v[142:143], v[102:103], v[94:95]
	v_pk_fma_f32 v[96:97], v[144:145], v[104:105], v[96:97]
	v_lshl_add_u64 v[100:101], s[8:9], 0, v[100:101]
	v_cndmask_b32_e32 v97, v97, v149, vcc
	v_cndmask_b32_e32 v96, v96, v149, vcc
	v_cndmask_b32_e32 v95, v95, v149, vcc
	v_cndmask_b32_e32 v94, v94, v149, vcc
	v_lshl_add_u64 v[100:101], v[100:101], 0, v[126:127]
	global_store_dwordx4 v[100:101], v[94:97], off
	v_pk_mul_f32 v[92:93], v[92:93], v[98:99] op_sel_hi:[1,0]
	v_pk_mul_f32 v[90:91], v[90:91], v[98:99] op_sel_hi:[1,0]
	v_lshlrev_b32_e32 v94, 16, v194
	v_and_b32_e32 v95, 0xffff0000, v194
	v_lshlrev_b32_e32 v96, 16, v195
	v_and_b32_e32 v97, 0xffff0000, v195
	v_pk_fma_f32 v[90:91], v[138:139], v[90:91], v[94:95]
	v_pk_fma_f32 v[92:93], v[140:141], v[92:93], v[96:97]
	v_cndmask_b32_e32 v91, v91, v149, vcc
	v_cndmask_b32_e32 v93, v93, v149, vcc
	v_cndmask_b32_e32 v92, v92, v149, vcc
	v_cndmask_b32_e32 v90, v90, v149, vcc
	global_store_dwordx4 v[100:101], v[90:93], off offset:64
	v_pk_mul_f32 v[84:85], v[84:85], v[98:99] op_sel_hi:[1,0]
	v_pk_mul_f32 v[82:83], v[82:83], v[98:99] op_sel_hi:[1,0]
	v_lshlrev_b32_e32 v90, 16, v192
	v_and_b32_e32 v91, 0xffff0000, v192
	v_lshlrev_b32_e32 v92, 16, v193
	v_and_b32_e32 v93, 0xffff0000, v193
	v_pk_fma_f32 v[82:83], v[134:135], v[82:83], v[90:91]
	v_pk_fma_f32 v[84:85], v[136:137], v[84:85], v[92:93]
	v_cndmask_b32_e32 v83, v83, v149, vcc
	v_cndmask_b32_e32 v85, v85, v149, vcc
	v_cndmask_b32_e32 v84, v84, v149, vcc
	v_cndmask_b32_e32 v82, v82, v149, vcc
	global_store_dwordx4 v[100:101], v[82:85], off offset:512
	v_pk_mul_f32 v[80:81], v[80:81], v[98:99] op_sel_hi:[1,0]
	v_pk_mul_f32 v[78:79], v[78:79], v[98:99] op_sel_hi:[1,0]
	v_lshlrev_b32_e32 v82, 16, v190
	v_and_b32_e32 v83, 0xffff0000, v190
	v_lshlrev_b32_e32 v84, 16, v191
	v_and_b32_e32 v85, 0xffff0000, v191
	v_pk_fma_f32 v[78:79], v[130:131], v[78:79], v[82:83]
	v_pk_fma_f32 v[80:81], v[132:133], v[80:81], v[84:85]
	v_cndmask_b32_e32 v79, v79, v149, vcc
	v_cndmask_b32_e32 v81, v81, v149, vcc
	v_cndmask_b32_e32 v80, v80, v149, vcc
	v_cndmask_b32_e32 v78, v78, v149, vcc
	global_store_dwordx4 v[100:101], v[78:81], off offset:576
	v_mov_b32_e32 v84, v99
	v_pk_mul_f32 v[88:89], v[88:89], v[84:85] op_sel_hi:[1,0]
	v_add_u32_e32 v78, 48, v222
	v_ashrrev_i32_e32 v79, 31, v78
	v_lshlrev_b64 v[82:83], 12, v[78:79]
	v_lshlrev_b32_e32 v78, 16, v188
	v_and_b32_e32 v79, 0xffff0000, v188
	v_lshlrev_b32_e32 v80, 16, v189
	v_and_b32_e32 v81, 0xffff0000, v189
	v_pk_mul_f32 v[86:87], v[86:87], v[84:85] op_sel_hi:[1,0]
	v_pk_fma_f32 v[80:81], v[144:145], v[88:89], v[80:81]
	v_pk_fma_f32 v[78:79], v[142:143], v[86:87], v[78:79]
	v_lshl_add_u64 v[82:83], s[8:9], 0, v[82:83]
	v_cndmask_b32_e32 v81, v81, v149, vcc
	v_cndmask_b32_e32 v80, v80, v149, vcc
	v_cndmask_b32_e32 v79, v79, v149, vcc
	v_cndmask_b32_e32 v78, v78, v149, vcc
	v_lshl_add_u64 v[82:83], v[82:83], 0, v[126:127]
	global_store_dwordx4 v[82:83], v[78:81], off
	v_pk_mul_f32 v[76:77], v[76:77], v[84:85] op_sel_hi:[1,0]
	v_pk_mul_f32 v[74:75], v[74:75], v[84:85] op_sel_hi:[1,0]
	v_lshlrev_b32_e32 v78, 16, v186
	v_and_b32_e32 v79, 0xffff0000, v186
	v_lshlrev_b32_e32 v80, 16, v187
	v_and_b32_e32 v81, 0xffff0000, v187
	v_pk_fma_f32 v[74:75], v[138:139], v[74:75], v[78:79]
	v_pk_fma_f32 v[76:77], v[140:141], v[76:77], v[80:81]
	v_cndmask_b32_e32 v75, v75, v149, vcc
	v_cndmask_b32_e32 v77, v77, v149, vcc
	v_cndmask_b32_e32 v76, v76, v149, vcc
	v_cndmask_b32_e32 v74, v74, v149, vcc
	global_store_dwordx4 v[82:83], v[74:77], off offset:64
	v_pk_mul_f32 v[72:73], v[72:73], v[84:85] op_sel_hi:[1,0]
	v_pk_mul_f32 v[70:71], v[70:71], v[84:85] op_sel_hi:[1,0]
	v_lshlrev_b32_e32 v74, 16, v184
	v_and_b32_e32 v75, 0xffff0000, v184
	v_lshlrev_b32_e32 v76, 16, v185
	v_and_b32_e32 v77, 0xffff0000, v185
	v_pk_fma_f32 v[70:71], v[134:135], v[70:71], v[74:75]
	v_pk_fma_f32 v[72:73], v[136:137], v[72:73], v[76:77]
	v_cndmask_b32_e32 v71, v71, v149, vcc
	v_cndmask_b32_e32 v73, v73, v149, vcc
	v_cndmask_b32_e32 v72, v72, v149, vcc
	v_cndmask_b32_e32 v70, v70, v149, vcc
	global_store_dwordx4 v[82:83], v[70:73], off offset:512
	v_pk_mul_f32 v[68:69], v[68:69], v[84:85] op_sel_hi:[1,0]
	v_pk_mul_f32 v[66:67], v[66:67], v[84:85] op_sel_hi:[1,0]
	v_lshlrev_b32_e32 v70, 16, v182
	v_and_b32_e32 v71, 0xffff0000, v182
	v_lshlrev_b32_e32 v72, 16, v183
	v_and_b32_e32 v73, 0xffff0000, v183
	v_pk_fma_f32 v[66:67], v[130:131], v[66:67], v[70:71]
	v_pk_fma_f32 v[68:69], v[132:133], v[68:69], v[72:73]
	v_cndmask_b32_e32 v67, v67, v149, vcc
	v_cndmask_b32_e32 v69, v69, v149, vcc
	v_cndmask_b32_e32 v68, v68, v149, vcc
	v_cndmask_b32_e32 v66, v66, v149, vcc
	global_store_dwordx4 v[82:83], v[66:69], off offset:576
	s_addk_i32 s24, 0x80
	v_or_b32_e32 v1, s24, v221
	v_add_u32_e32 v66, 0x2000, v148
	ds_read2_b32 v[66:67], v66 offset0:128 offset1:144
	v_add_u32_e32 v68, s27, v1
	v_ashrrev_i32_e32 v69, 31, v68
	v_lshlrev_b64 v[70:71], 12, v[68:69]
	v_lshlrev_b32_e32 v72, 16, v180
	v_and_b32_e32 v73, 0xffff0000, v180
	v_lshlrev_b32_e32 v74, 16, v181
	v_and_b32_e32 v75, 0xffff0000, v181
	s_waitcnt lgkmcnt(0)
	v_pk_mul_f32 v[64:65], v[64:65], v[66:67] op_sel_hi:[1,0]
	v_pk_mul_f32 v[62:63], v[62:63], v[66:67] op_sel_hi:[1,0]
	v_pk_fma_f32 v[64:65], v[144:145], v[64:65], v[74:75]
	v_pk_fma_f32 v[62:63], v[142:143], v[62:63], v[72:73]
	v_lshl_add_u64 v[70:71], s[8:9], 0, v[70:71]
	v_cndmask_b32_e32 v65, v65, v149, vcc
	v_cndmask_b32_e32 v64, v64, v149, vcc
	v_cndmask_b32_e32 v63, v63, v149, vcc
	v_cndmask_b32_e32 v62, v62, v149, vcc
	v_lshl_add_u64 v[70:71], v[70:71], 0, v[126:127]
	global_store_dwordx4 v[70:71], v[62:65], off
	v_pk_mul_f32 v[60:61], v[60:61], v[66:67] op_sel_hi:[1,0]
	v_pk_mul_f32 v[58:59], v[58:59], v[66:67] op_sel_hi:[1,0]
	v_lshlrev_b32_e32 v62, 16, v178
	v_and_b32_e32 v63, 0xffff0000, v178
	v_lshlrev_b32_e32 v64, 16, v179
	v_and_b32_e32 v65, 0xffff0000, v179
	v_pk_fma_f32 v[60:61], v[140:141], v[60:61], v[64:65]
	v_pk_fma_f32 v[58:59], v[138:139], v[58:59], v[62:63]
	v_cndmask_b32_e32 v61, v61, v149, vcc
	v_cndmask_b32_e32 v60, v60, v149, vcc
	v_cndmask_b32_e32 v59, v59, v149, vcc
	v_cndmask_b32_e32 v58, v58, v149, vcc
	global_store_dwordx4 v[70:71], v[58:61], off offset:64
	v_pk_mul_f32 v[52:53], v[52:53], v[66:67] op_sel_hi:[1,0]
	v_pk_mul_f32 v[50:51], v[50:51], v[66:67] op_sel_hi:[1,0]
	v_lshlrev_b32_e32 v58, 16, v176
	v_and_b32_e32 v59, 0xffff0000, v176
	v_lshlrev_b32_e32 v60, 16, v177
	v_and_b32_e32 v61, 0xffff0000, v177
	v_pk_fma_f32 v[52:53], v[136:137], v[52:53], v[60:61]
	v_pk_fma_f32 v[50:51], v[134:135], v[50:51], v[58:59]
	v_cndmask_b32_e32 v53, v53, v149, vcc
	v_cndmask_b32_e32 v52, v52, v149, vcc
	v_cndmask_b32_e32 v51, v51, v149, vcc
	v_cndmask_b32_e32 v50, v50, v149, vcc
	global_store_dwordx4 v[70:71], v[50:53], off offset:512
	v_pk_mul_f32 v[48:49], v[48:49], v[66:67] op_sel_hi:[1,0]
	v_pk_mul_f32 v[46:47], v[46:47], v[66:67] op_sel_hi:[1,0]
	v_lshlrev_b32_e32 v50, 16, v174
	v_and_b32_e32 v51, 0xffff0000, v174
	v_lshlrev_b32_e32 v52, 16, v175
	v_and_b32_e32 v53, 0xffff0000, v175
	v_pk_fma_f32 v[48:49], v[132:133], v[48:49], v[52:53]
	v_pk_fma_f32 v[46:47], v[130:131], v[46:47], v[50:51]
	v_cndmask_b32_e32 v49, v49, v149, vcc
	v_cndmask_b32_e32 v48, v48, v149, vcc
	v_cndmask_b32_e32 v47, v47, v149, vcc
	v_cndmask_b32_e32 v46, v46, v149, vcc
	global_store_dwordx4 v[70:71], v[46:49], off offset:576
	v_mov_b32_e32 v52, v67
	v_pk_mul_f32 v[56:57], v[56:57], v[52:53] op_sel_hi:[1,0]
	v_add_u32_e32 v46, 16, v68
	v_ashrrev_i32_e32 v47, 31, v46
	v_lshlrev_b64 v[50:51], 12, v[46:47]
	v_lshlrev_b32_e32 v46, 16, v172
	v_and_b32_e32 v47, 0xffff0000, v172
	v_lshlrev_b32_e32 v48, 16, v173
	v_and_b32_e32 v49, 0xffff0000, v173
	v_pk_mul_f32 v[54:55], v[54:55], v[52:53] op_sel_hi:[1,0]
	v_pk_fma_f32 v[48:49], v[144:145], v[56:57], v[48:49]
	v_pk_fma_f32 v[46:47], v[142:143], v[54:55], v[46:47]
	v_lshl_add_u64 v[50:51], s[8:9], 0, v[50:51]
	v_cndmask_b32_e32 v49, v49, v149, vcc
	v_cndmask_b32_e32 v48, v48, v149, vcc
	v_cndmask_b32_e32 v47, v47, v149, vcc
	v_cndmask_b32_e32 v46, v46, v149, vcc
	v_lshl_add_u64 v[50:51], v[50:51], 0, v[126:127]
	global_store_dwordx4 v[50:51], v[46:49], off
	v_pk_mul_f32 v[44:45], v[44:45], v[52:53] op_sel_hi:[1,0]
	v_pk_mul_f32 v[42:43], v[42:43], v[52:53] op_sel_hi:[1,0]
	v_lshlrev_b32_e32 v46, 16, v170
	v_and_b32_e32 v47, 0xffff0000, v170
	v_lshlrev_b32_e32 v48, 16, v171
	v_and_b32_e32 v49, 0xffff0000, v171
	v_pk_fma_f32 v[44:45], v[140:141], v[44:45], v[48:49]
	v_pk_fma_f32 v[42:43], v[138:139], v[42:43], v[46:47]
	v_cndmask_b32_e32 v45, v45, v149, vcc
	v_cndmask_b32_e32 v44, v44, v149, vcc
	v_cndmask_b32_e32 v43, v43, v149, vcc
	v_cndmask_b32_e32 v42, v42, v149, vcc
	global_store_dwordx4 v[50:51], v[42:45], off offset:64
	v_pk_mul_f32 v[36:37], v[36:37], v[52:53] op_sel_hi:[1,0]
	v_pk_mul_f32 v[34:35], v[34:35], v[52:53] op_sel_hi:[1,0]
	v_lshlrev_b32_e32 v42, 16, v168
	v_and_b32_e32 v43, 0xffff0000, v168
	v_lshlrev_b32_e32 v44, 16, v169
	v_and_b32_e32 v45, 0xffff0000, v169
	v_pk_fma_f32 v[36:37], v[136:137], v[36:37], v[44:45]
	v_pk_fma_f32 v[34:35], v[134:135], v[34:35], v[42:43]
	v_cndmask_b32_e32 v37, v37, v149, vcc
	v_cndmask_b32_e32 v36, v36, v149, vcc
	v_cndmask_b32_e32 v35, v35, v149, vcc
	v_cndmask_b32_e32 v34, v34, v149, vcc
	global_store_dwordx4 v[50:51], v[34:37], off offset:512
	v_pk_mul_f32 v[32:33], v[32:33], v[52:53] op_sel_hi:[1,0]
	v_pk_mul_f32 v[30:31], v[30:31], v[52:53] op_sel_hi:[1,0]
	v_lshlrev_b32_e32 v34, 16, v166
	v_and_b32_e32 v35, 0xffff0000, v166
	v_lshlrev_b32_e32 v36, 16, v167
	v_and_b32_e32 v37, 0xffff0000, v167
	v_pk_fma_f32 v[32:33], v[132:133], v[32:33], v[36:37]
	v_pk_fma_f32 v[30:31], v[130:131], v[30:31], v[34:35]
	v_cndmask_b32_e32 v33, v33, v149, vcc
	v_cndmask_b32_e32 v32, v32, v149, vcc
	v_cndmask_b32_e32 v31, v31, v149, vcc
	v_cndmask_b32_e32 v30, v30, v149, vcc
	global_store_dwordx4 v[50:51], v[30:33], off offset:576
	v_pk_mul_f32 v[36:37], v[40:41], v[0:1] op_sel_hi:[1,0]
	v_pk_mul_f32 v[38:39], v[38:39], v[0:1] op_sel_hi:[1,0]
	v_add_u32_e32 v30, 32, v68
	v_ashrrev_i32_e32 v31, 31, v30
	v_lshlrev_b64 v[34:35], 12, v[30:31]
	v_lshlrev_b32_e32 v30, 16, v164
	v_and_b32_e32 v31, 0xffff0000, v164
	v_lshlrev_b32_e32 v32, 16, v165
	v_and_b32_e32 v33, 0xffff0000, v165
	v_pk_fma_f32 v[30:31], v[142:143], v[38:39], v[30:31]
	v_pk_fma_f32 v[32:33], v[144:145], v[36:37], v[32:33]
	v_lshl_add_u64 v[34:35], s[8:9], 0, v[34:35]
	v_cndmask_b32_e32 v33, v33, v149, vcc
	v_cndmask_b32_e32 v32, v32, v149, vcc
	v_cndmask_b32_e32 v31, v31, v149, vcc
	v_cndmask_b32_e32 v30, v30, v149, vcc
	v_lshl_add_u64 v[34:35], v[34:35], 0, v[126:127]
	global_store_dwordx4 v[34:35], v[30:33], off
	v_pk_mul_f32 v[28:29], v[28:29], v[0:1] op_sel_hi:[1,0]
	v_pk_mul_f32 v[26:27], v[26:27], v[0:1] op_sel_hi:[1,0]
	v_lshlrev_b32_e32 v30, 16, v162
	v_and_b32_e32 v31, 0xffff0000, v162
	v_lshlrev_b32_e32 v32, 16, v163
	v_and_b32_e32 v33, 0xffff0000, v163
	v_pk_fma_f32 v[26:27], v[138:139], v[26:27], v[30:31]
	v_pk_fma_f32 v[28:29], v[140:141], v[28:29], v[32:33]
	v_cndmask_b32_e32 v27, v27, v149, vcc
	v_cndmask_b32_e32 v29, v29, v149, vcc
	v_cndmask_b32_e32 v28, v28, v149, vcc
	v_cndmask_b32_e32 v26, v26, v149, vcc
	global_store_dwordx4 v[34:35], v[26:29], off offset:64
	v_pk_mul_f32 v[24:25], v[24:25], v[0:1] op_sel_hi:[1,0]
	v_pk_mul_f32 v[22:23], v[22:23], v[0:1] op_sel_hi:[1,0]
	v_lshlrev_b32_e32 v26, 16, v160
	v_and_b32_e32 v27, 0xffff0000, v160
	v_lshlrev_b32_e32 v28, 16, v161
	v_and_b32_e32 v29, 0xffff0000, v161
	v_pk_fma_f32 v[22:23], v[134:135], v[22:23], v[26:27]
	v_pk_fma_f32 v[24:25], v[136:137], v[24:25], v[28:29]
	v_cndmask_b32_e32 v23, v23, v149, vcc
	v_cndmask_b32_e32 v25, v25, v149, vcc
	v_cndmask_b32_e32 v24, v24, v149, vcc
	v_cndmask_b32_e32 v22, v22, v149, vcc
	global_store_dwordx4 v[34:35], v[22:25], off offset:512
	v_pk_mul_f32 v[16:17], v[16:17], v[0:1] op_sel_hi:[1,0]
	v_pk_mul_f32 v[0:1], v[14:15], v[0:1] op_sel_hi:[1,0]
	v_lshlrev_b32_e32 v22, 16, v158
	v_and_b32_e32 v23, 0xffff0000, v158
	v_lshlrev_b32_e32 v24, 16, v159
	v_and_b32_e32 v25, 0xffff0000, v159
	v_pk_fma_f32 v[0:1], v[130:131], v[0:1], v[22:23]
	v_pk_fma_f32 v[14:15], v[132:133], v[16:17], v[24:25]
	v_pk_mul_f32 v[20:21], v[20:21], v[146:147] op_sel_hi:[1,0]
	v_cndmask_b32_e32 v16, v14, v149, vcc
	v_cndmask_b32_e32 v14, v0, v149, vcc
	v_add_u32_e32 v0, 48, v68
	v_cndmask_b32_e32 v17, v15, v149, vcc
	v_cndmask_b32_e32 v15, v1, v149, vcc
	v_ashrrev_i32_e32 v1, 31, v0
	global_store_dwordx4 v[34:35], v[14:17], off offset:576
	v_lshlrev_b64 v[0:1], 12, v[0:1]
	v_pk_mul_f32 v[18:19], v[18:19], v[146:147] op_sel_hi:[1,0]
	v_lshlrev_b32_e32 v14, 16, v156
	v_and_b32_e32 v15, 0xffff0000, v156
	v_lshlrev_b32_e32 v16, 16, v157
	v_and_b32_e32 v17, 0xffff0000, v157
	v_pk_fma_f32 v[16:17], v[144:145], v[20:21], v[16:17]
	v_pk_fma_f32 v[14:15], v[142:143], v[18:19], v[14:15]
	v_lshl_add_u64 v[0:1], s[8:9], 0, v[0:1]
	v_cndmask_b32_e32 v17, v17, v149, vcc
	v_cndmask_b32_e32 v16, v16, v149, vcc
	v_cndmask_b32_e32 v15, v15, v149, vcc
	v_cndmask_b32_e32 v14, v14, v149, vcc
	v_lshl_add_u64 v[18:19], v[0:1], 0, v[126:127]
	global_store_dwordx4 v[18:19], v[14:17], off
	v_lshlrev_b32_e32 v0, 16, v154
	v_and_b32_e32 v1, 0xffff0000, v154
	v_lshlrev_b32_e32 v14, 16, v155
	v_and_b32_e32 v15, 0xffff0000, v155
	v_pk_mul_f32 v[12:13], v[12:13], v[146:147] op_sel_hi:[1,0]
	v_pk_mul_f32 v[10:11], v[10:11], v[146:147] op_sel_hi:[1,0]
	v_pk_fma_f32 v[12:13], v[140:141], v[12:13], v[14:15]
	v_pk_fma_f32 v[0:1], v[138:139], v[10:11], v[0:1]
	v_cndmask_b32_e32 v13, v13, v149, vcc
	v_cndmask_b32_e32 v12, v12, v149, vcc
	v_cndmask_b32_e32 v11, v1, v149, vcc
	v_cndmask_b32_e32 v10, v0, v149, vcc
	global_store_dwordx4 v[18:19], v[10:13], off offset:64
	v_lshlrev_b32_e32 v0, 16, v152
	v_and_b32_e32 v1, 0xffff0000, v152
	v_lshlrev_b32_e32 v10, 16, v153
	v_and_b32_e32 v11, 0xffff0000, v153
	v_pk_mul_f32 v[8:9], v[8:9], v[146:147] op_sel_hi:[1,0]
	v_pk_mul_f32 v[6:7], v[6:7], v[146:147] op_sel_hi:[1,0]
	v_pk_fma_f32 v[8:9], v[136:137], v[8:9], v[10:11]
	v_pk_fma_f32 v[0:1], v[134:135], v[6:7], v[0:1]
	v_cndmask_b32_e32 v9, v9, v149, vcc
	v_cndmask_b32_e32 v8, v8, v149, vcc
	v_cndmask_b32_e32 v7, v1, v149, vcc
	v_cndmask_b32_e32 v6, v0, v149, vcc
	global_store_dwordx4 v[18:19], v[6:9], off offset:512
	v_lshlrev_b32_e32 v0, 16, v150
	v_and_b32_e32 v1, 0xffff0000, v150
	v_lshlrev_b32_e32 v6, 16, v151
	v_and_b32_e32 v7, 0xffff0000, v151
	v_pk_mul_f32 v[4:5], v[4:5], v[146:147] op_sel_hi:[1,0]
	v_pk_mul_f32 v[2:3], v[2:3], v[146:147] op_sel_hi:[1,0]
	v_pk_fma_f32 v[4:5], v[132:133], v[4:5], v[6:7]
	v_pk_fma_f32 v[0:1], v[130:131], v[2:3], v[0:1]
	v_cndmask_b32_e32 v3, v5, v149, vcc
	v_cndmask_b32_e32 v2, v4, v149, vcc
	v_cndmask_b32_e32 v1, v1, v149, vcc
	v_cndmask_b32_e32 v0, v0, v149, vcc
	global_store_dwordx4 v[128:129], v[214:217], off
	global_store_dwordx4 v[18:19], v[0:3], off offset:576
	s_endpgm

	.amdhsa_kernel _Z3fwd4Args
		.amdhsa_group_segment_fixed_size 0
		.amdhsa_private_segment_fixed_size 0
		.amdhsa_kernarg_size 408
		.amdhsa_user_sgpr_count 2
		.amdhsa_user_sgpr_dispatch_ptr 0
		.amdhsa_user_sgpr_queue_ptr 0
		.amdhsa_user_sgpr_kernarg_segment_ptr 1
		.amdhsa_user_sgpr_dispatch_id 0
		.amdhsa_user_sgpr_kernarg_preload_length 0
		.amdhsa_user_sgpr_kernarg_preload_offset 0
		.amdhsa_user_sgpr_private_segment_size 0
		.amdhsa_uses_dynamic_stack 0
		.amdhsa_enable_private_segment 0
		.amdhsa_system_sgpr_workgroup_id_x 1
		.amdhsa_system_sgpr_workgroup_id_y 0
		.amdhsa_system_sgpr_workgroup_id_z 0
		.amdhsa_system_sgpr_workgroup_info 0
		.amdhsa_system_vgpr_workitem_id 0
		.amdhsa_next_free_vgpr 256
		.amdhsa_next_free_sgpr 98
		.amdhsa_accum_offset 256
		.amdhsa_reserve_vcc 1
		.amdhsa_float_round_mode_32 0
		.amdhsa_float_round_mode_16_64 0
		.amdhsa_float_denorm_mode_32 3
		.amdhsa_float_denorm_mode_16_64 3
		.amdhsa_dx10_clamp 1
		.amdhsa_ieee_mode 1
		.amdhsa_fp16_overflow 0
		.amdhsa_tg_split 0
		.amdhsa_exception_fp_ieee_invalid_op 0
		.amdhsa_exception_fp_denorm_src 0
		.amdhsa_exception_fp_ieee_div_zero 0
		.amdhsa_exception_fp_ieee_overflow 0
		.amdhsa_exception_fp_ieee_underflow 0
		.amdhsa_exception_fp_ieee_inexact 0
		.amdhsa_exception_int_div_zero 0
	.end_amdhsa_kernel

.Lfunc_end0:
	.size	_Z3fwd4Args, .Lfunc_end0-_Z3fwd4Args
	.set _Z3fwd4Args.num_vgpr, 256
	.set _Z3fwd4Args.num_agpr, 0
	.set _Z3fwd4Args.numbered_sgpr, 98
	.set _Z3fwd4Args.num_named_barrier, 0
	.set _Z3fwd4Args.private_seg_size, 0
	.set _Z3fwd4Args.uses_vcc, 1
	.set _Z3fwd4Args.uses_flat_scratch, 0
	.set _Z3fwd4Args.has_dyn_sized_stack, 0
	.set _Z3fwd4Args.has_recursion, 0
	.set _Z3fwd4Args.has_indirect_call, 0

amdhsa.kernels:
  - .agpr_count:     0
    .args:
      - .offset:         0
        .size:           152
        .value_kind:     by_value
      - .offset:         152
        .size:           4
        .value_kind:     hidden_block_count_x
      - .offset:         156
        .size:           4
        .value_kind:     hidden_block_count_y
      - .offset:         160
        .size:           4
        .value_kind:     hidden_block_count_z
      - .offset:         164
        .size:           2
        .value_kind:     hidden_group_size_x
      - .offset:         166
        .size:           2
        .value_kind:     hidden_group_size_y
      - .offset:         168
        .size:           2
        .value_kind:     hidden_group_size_z
      - .offset:         170
        .size:           2
        .value_kind:     hidden_remainder_x
      - .offset:         172
        .size:           2
        .value_kind:     hidden_remainder_y
      - .offset:         174
        .size:           2
        .value_kind:     hidden_remainder_z
      - .offset:         192
        .size:           8
        .value_kind:     hidden_global_offset_x
      - .offset:         200
        .size:           8
        .value_kind:     hidden_global_offset_y
      - .offset:         208
        .size:           8
        .value_kind:     hidden_global_offset_z
      - .offset:         216
        .size:           2
        .value_kind:     hidden_grid_dims
      - .offset:         272
        .size:           4
        .value_kind:     hidden_dynamic_lds_size
    .group_segment_fixed_size: 0
    .kernarg_segment_align: 8
    .kernarg_segment_size: 408
    .language:       OpenCL C
    .language_version:
      - 2
      - 0
    .max_flat_workgroup_size: 512
    .name:           _Z3fwd4Args
    .private_segment_fixed_size: 0
    .sgpr_count:     104
    .sgpr_spill_count: 65
    .symbol:         _Z3fwd4Args.kd
    .uniform_work_group_size: 1
    .uses_dynamic_stack: false
    .vgpr_count:     256
    .vgpr_spill_count: 0
    .wavefront_size: 64
